# GDN scan step: the per-step mask re-derivation (v_cndmask + v_cmp_ne) replaced by one s_andn2_b64 (exact)
# baseline (speedup 1.0000x reference)
.LBB0_524:
	s_waitcnt lgkmcnt(0)
	s_barrier
	v_mov_b32_e32 v18, 0
	s_andn2_b64 s[0:1], exec, s[12:13]
	s_andn2_b64 vcc, exec, s[12:13]
	v_mov_b32_e32 v19, 0
	v_mov_b32_e32 v20, 0
	v_mov_b32_e32 v21, 0
	v_mov_b32_e32 v22, 0
	v_mov_b32_e32 v23, 0
	v_mov_b32_e32 v24, 0
	v_mov_b32_e32 v25, 0
	v_mov_b32_e32 v26, 0
	v_mov_b32_e32 v27, 0
	v_mov_b32_e32 v28, 0
	v_mov_b32_e32 v29, 0
	v_mov_b32_e32 v30, 0
	v_mov_b32_e32 v31, 0
	v_mov_b32_e32 v32, 0
	v_mov_b32_e32 v33, 0
	s_cbranch_vccnz .LBB0_527
	v_add_u32_e32 v38, v149, v148
	ds_read_b128 v[18:21], v38
	ds_read_b128 v[34:37], v38 offset:32
	ds_read_b128 v[40:43], v38 offset:64
	ds_read_b128 v[44:47], v38 offset:96
	ds_read_b128 v[240:243], v38 offset:128
	ds_read_b128 v[244:247], v38 offset:160
	ds_read_b128 v[248:251], v38 offset:192
	s_andn2_b64 vcc, exec, s[4:5]
	s_waitcnt lgkmcnt(5)
	v_mfma_f32_32x32x16_bf16 v[18:33], v[142:145], v[18:21], 0
	v_mfma_f32_32x32x16_bf16 v[18:33], v[138:141], v[34:37], v[18:33]
	ds_read_b128 v[34:37], v38 offset:224
	s_waitcnt lgkmcnt(5)
	v_mfma_f32_32x32x16_bf16 v[18:33], v[134:137], v[40:43], v[18:33]
	s_waitcnt lgkmcnt(4)
	v_mfma_f32_32x32x16_bf16 v[18:33], v[130:133], v[44:47], v[18:33]
	s_waitcnt lgkmcnt(3)
	v_mfma_f32_32x32x16_bf16 v[18:33], v[126:129], v[240:243], v[18:33]
	s_waitcnt lgkmcnt(2)
	v_mfma_f32_32x32x16_bf16 v[18:33], v[122:125], v[244:247], v[18:33]
	s_waitcnt lgkmcnt(1)
	v_mfma_f32_32x32x16_bf16 v[18:33], v[118:121], v[248:251], v[18:33]
	s_waitcnt lgkmcnt(0)
	v_mfma_f32_32x32x16_bf16 v[18:33], v[114:117], v[34:37], v[18:33]
	s_cbranch_vccnz .LBB0_527
	v_lshlrev_b32_e32 v34, 16, v216
	v_and_b32_e32 v35, 0xffff0000, v216
	v_lshlrev_b32_e32 v36, 16, v217
	v_and_b32_e32 v37, 0xffff0000, v217
	s_nop 6
	v_pk_add_f32 v[34:35], v[34:35], v[18:19] neg_lo:[0,1] neg_hi:[0,1]
	v_pk_add_f32 v[36:37], v[36:37], v[20:21] neg_lo:[0,1] neg_hi:[0,1]
	v_cvt_pk_bf16_f32 v34, v34, v35
	v_cvt_pk_bf16_f32 v35, v36, v37
	v_lshlrev_b32_e32 v36, 16, v214
	v_and_b32_e32 v37, 0xffff0000, v214
	v_lshlrev_b32_e32 v38, 16, v215
	v_and_b32_e32 v39, 0xffff0000, v215
	v_add_u32_e32 v40, v167, v146
	v_pk_add_f32 v[36:37], v[36:37], v[22:23] neg_lo:[0,1] neg_hi:[0,1]
	v_pk_add_f32 v[38:39], v[38:39], v[24:25] neg_lo:[0,1] neg_hi:[0,1]
	v_cvt_pk_bf16_f32 v36, v36, v37
	v_cvt_pk_bf16_f32 v37, v38, v39
	v_add_u32_e32 v40, 0x2000, v40
	ds_write2_b64 v40, v[34:35], v[36:37] offset0:64 offset1:66
	v_lshlrev_b32_e32 v34, 16, v212
	v_and_b32_e32 v35, 0xffff0000, v212
	v_lshlrev_b32_e32 v36, 16, v213
	v_and_b32_e32 v37, 0xffff0000, v213
	v_pk_add_f32 v[34:35], v[34:35], v[26:27] neg_lo:[0,1] neg_hi:[0,1]
	v_pk_add_f32 v[36:37], v[36:37], v[28:29] neg_lo:[0,1] neg_hi:[0,1]
	v_cvt_pk_bf16_f32 v34, v34, v35
	v_cvt_pk_bf16_f32 v35, v36, v37
	v_lshlrev_b32_e32 v36, 16, v210
	v_and_b32_e32 v37, 0xffff0000, v210
	v_lshlrev_b32_e32 v38, 16, v211
	v_and_b32_e32 v39, 0xffff0000, v211
	v_pk_add_f32 v[36:37], v[36:37], v[30:31] neg_lo:[0,1] neg_hi:[0,1]
	v_pk_add_f32 v[38:39], v[38:39], v[32:33] neg_lo:[0,1] neg_hi:[0,1]
	v_cvt_pk_bf16_f32 v36, v36, v37
	v_cvt_pk_bf16_f32 v37, v38, v39
	ds_write2_b64 v40, v[34:35], v[36:37] offset0:68 offset1:70
